# stack7 (f1 single K iteration: A zero for k>=128) + nt hint on the weight-transposes f32 loads
# baseline (speedup 1.0000x reference)
.LBB1_26:
	s_mul_hi_i32 s14, s25, 0x82082083
	s_add_i32 s14, s14, s25
	s_lshr_b32 s15, s14, 31
	s_ashr_i32 s14, s14, 14
	s_add_i32 s14, s14, s15
	s_mul_i32 s15, s14, 0xffff8200
	s_add_i32 s49, s25, s15
	s_ashr_i32 s15, s14, 31
	s_mul_i32 s17, s14, 0x7e00000
	s_mul_hi_i32 s16, s14, 0x7e00000
	s_add_u32 s47, s27, s17
	s_addc_u32 s48, s28, s16
	s_cmpk_gt_i32 s49, 0x2bff
	s_mov_b64 s[16:17], -1
	s_cbranch_scc0 .LBB1_48
	s_cmpk_gt_u32 s49, 0x57ff
	s_cbranch_scc0 .LBB1_45
	s_cmpk_gt_u32 s49, 0x59ff
	s_cbranch_scc0 .LBB1_42
	s_cmpk_gt_u32 s49, 0x5bff
	s_cbranch_scc0 .LBB1_39
	s_cmpk_gt_u32 s49, 0x5fff
	s_cbranch_scc0 .LBB1_36
	s_and_b32 s50, s29, 0x7e0
	s_cmpk_gt_u32 s49, 0x67ff
	v_or_b32_e32 v29, s50, v6
	v_or_b32_e32 v28, s50, v7
	v_or_b32_e32 v27, s50, v8
	v_or_b32_e32 v26, s50, v9
	s_cbranch_scc0 .LBB1_33
	v_readlane_b32 s52, v253, 0
	s_mul_i32 s17, s14, 0x2c00000
	v_readlane_b32 s56, v253, 4
	s_mul_hi_i32 s16, s14, 0x2c00000
	v_readlane_b32 s57, v253, 5
	s_add_u32 s17, s56, s17
	s_addc_u32 s51, s57, s16
	s_add_i32 s16, s49, 0x9800
	s_and_b32 s52, s16, 0xffc0
	s_lshl_b32 s16, s50, 2
	s_add_u32 s16, s17, s16
	v_or_b32_e32 v5, s52, v6
	s_addc_u32 s17, s51, 0
	v_lshl_add_u64 v[30:31], s[16:17], 0, v[2:3]
	v_lshlrev_b32_e32 v32, 13, v5
	v_mov_b32_e32 v33, v3
	v_lshl_add_u64 v[58:59], v[30:31], 0, v[32:33]
	v_add_co_u32_e32 v34, vcc, s31, v58
	s_lshl_b32 s16, s52, 1
	s_nop 0
	v_addc_co_u32_e32 v35, vcc, 0, v59, vcc
	v_add_co_u32_e32 v38, vcc, s34, v58
	global_load_dwordx4 v[30:33], v[58:59], off nt
	s_nop 0
	global_load_dwordx4 v[34:37], v[34:35], off nt
	v_addc_co_u32_e32 v39, vcc, 0, v59, vcc
	v_add_co_u32_e32 v42, vcc, s35, v58
	s_add_u32 s16, s47, s16
	s_nop 0
	v_addc_co_u32_e32 v43, vcc, 0, v59, vcc
	v_add_co_u32_e32 v46, vcc, s36, v58
	global_load_dwordx4 v[38:41], v[38:39], off nt
	s_nop 0
	global_load_dwordx4 v[42:45], v[42:43], off nt
	v_addc_co_u32_e32 v47, vcc, 0, v59, vcc
	v_add_co_u32_e32 v50, vcc, s37, v58
	v_mov_b32_e32 v5, v3
	s_nop 0
	v_addc_co_u32_e32 v51, vcc, 0, v59, vcc
	global_load_dwordx4 v[46:49], v[46:47], off nt
	s_nop 0
	global_load_dwordx4 v[50:53], v[50:51], off nt
	v_add_co_u32_e32 v54, vcc, s38, v58
	s_addc_u32 s17, s48, 0
	s_nop 0
	v_addc_co_u32_e32 v55, vcc, 0, v59, vcc
	global_load_dwordx4 v[54:57], v[54:55], off nt
	v_add_co_u32_e32 v58, vcc, s39, v58
	v_mul_u32_u24_e32 v62, 0x1600, v29
	s_nop 0
	v_addc_co_u32_e32 v59, vcc, 0, v59, vcc
	global_load_dwordx4 v[58:61], v[58:59], off nt
	v_lshl_add_u64 v[66:67], s[16:17], 0, v[4:5]
	v_mov_b32_e32 v63, v3
	v_lshlrev_b32_e32 v62, 1, v62
	v_lshl_add_u64 v[66:67], v[66:67], 0, s[0:1]
	v_lshl_add_u64 v[62:63], v[66:67], 0, v[62:63]
	v_mul_u32_u24_e32 v64, 0x1600, v28
	v_mov_b32_e32 v65, v3
	v_lshlrev_b32_e32 v64, 1, v64
	v_mul_u32_u24_e32 v5, 0x1600, v27
	v_readlane_b32 s58, v253, 6
	v_readlane_b32 s59, v253, 7
	v_readlane_b32 s56, v253, 42
	v_readlane_b32 s57, v253, 43
	v_readlane_b32 s59, v253, 45
	v_readlane_b32 s53, v253, 1
	v_readlane_b32 s54, v253, 2
	v_readlane_b32 s55, v253, 3
	v_readlane_b32 s91, v253, 46
	v_readlane_b32 s58, v253, 44
	s_mov_b64 s[76:77], s[56:57]
	s_mov_b32 s79, s59
	s_mov_b64 s[16:17], 0
	s_waitcnt vmcnt(7)
	ds_write2_b32 v11, v30, v31 offset1:1
	ds_write2_b32 v11, v32, v33 offset0:2 offset1:3
	s_waitcnt vmcnt(6)
	ds_write2_b32 v12, v34, v35 offset1:1
	ds_write2_b32 v13, v36, v37 offset1:1
	s_waitcnt vmcnt(5)
	ds_write2_b32 v14, v38, v39 offset1:1
	ds_write2_b32 v15, v40, v41 offset1:1
	s_waitcnt vmcnt(4)
	ds_write2_b32 v16, v42, v43 offset1:1
	ds_write2_b32 v17, v44, v45 offset1:1
	s_waitcnt vmcnt(3)
	ds_write2_b32 v18, v46, v47 offset1:1
	ds_write2_b32 v19, v48, v49 offset1:1
	s_waitcnt vmcnt(2)
	ds_write2_b32 v20, v50, v51 offset1:1
	ds_write2_b32 v21, v52, v53 offset1:1
	s_waitcnt vmcnt(1)
	ds_write2_b32 v22, v54, v55 offset1:1
	ds_write2_b32 v23, v56, v57 offset1:1
	s_waitcnt vmcnt(0)
	ds_write2_b32 v24, v58, v59 offset1:1
	ds_write2_b32 v25, v60, v61 offset1:1
	s_waitcnt lgkmcnt(0)
	ds_read2_b32 v[34:35], v10 offset0:33 offset1:41
	ds_read2_b32 v[36:37], v10 offset1:8
	ds_read2_b32 v[38:39], v10 offset0:66 offset1:74
	ds_read2_b32 v[40:41], v10 offset0:99 offset1:107
	ds_read2_b32 v[42:43], v10 offset0:132 offset1:140
	ds_read2_b32 v[44:45], v10 offset0:165 offset1:173
	ds_read2_b32 v[46:47], v10 offset0:198 offset1:206
	ds_read2_b32 v[48:49], v10 offset0:231 offset1:239
	s_waitcnt lgkmcnt(6)
	v_cvt_pk_bf16_f32 v30, v36, v34
	s_waitcnt lgkmcnt(4)
	v_cvt_pk_bf16_f32 v31, v38, v40
	s_waitcnt lgkmcnt(2)
	v_cvt_pk_bf16_f32 v32, v42, v44
	v_cvt_pk_bf16_f32 v34, v37, v35
	s_waitcnt lgkmcnt(0)
	v_cvt_pk_bf16_f32 v33, v46, v48
	global_store_dwordx4 v[62:63], v[30:33], off
	v_cvt_pk_bf16_f32 v35, v39, v41
	v_cvt_pk_bf16_f32 v36, v43, v45
	v_cvt_pk_bf16_f32 v37, v47, v49
	ds_read2_b32 v[38:39], v10 offset0:16 offset1:24
	ds_read2_b32 v[40:41], v10 offset0:49 offset1:57
	ds_read2_b32 v[42:43], v10 offset0:82 offset1:90
	ds_read2_b32 v[44:45], v10 offset0:115 offset1:123
	ds_read2_b32 v[46:47], v10 offset0:148 offset1:156
	ds_read2_b32 v[48:49], v10 offset0:181 offset1:189
	ds_read2_b32 v[52:53], v10 offset0:214 offset1:222
	ds_read2_b32 v[54:55], v10 offset0:247 offset1:255
	v_lshl_add_u64 v[50:51], v[66:67], 0, v[64:65]
	global_store_dwordx4 v[50:51], v[34:37], off
	s_waitcnt lgkmcnt(6)
	v_cvt_pk_bf16_f32 v30, v38, v40
	s_waitcnt lgkmcnt(4)
	v_cvt_pk_bf16_f32 v31, v42, v44
	v_lshlrev_b32_e32 v34, 1, v5
	v_mov_b32_e32 v35, v3
	s_waitcnt lgkmcnt(2)
	v_cvt_pk_bf16_f32 v32, v46, v48
	s_waitcnt lgkmcnt(0)
	v_cvt_pk_bf16_f32 v33, v52, v54
	v_lshl_add_u64 v[34:35], v[66:67], 0, v[34:35]
	v_mul_u32_u24_e32 v5, 0x1600, v26
	global_store_dwordx4 v[34:35], v[30:33], off
	v_lshlrev_b32_e32 v34, 1, v5
	v_mov_b32_e32 v35, v3
	v_cvt_pk_bf16_f32 v30, v39, v41
	v_cvt_pk_bf16_f32 v31, v43, v45
	v_cvt_pk_bf16_f32 v32, v47, v49
	v_cvt_pk_bf16_f32 v33, v53, v55
	v_lshl_add_u64 v[34:35], v[66:67], 0, v[34:35]
	global_store_dwordx4 v[34:35], v[30:33], off
	s_waitcnt lgkmcnt(0)
.LBB1_33:
	s_andn2_b64 vcc, exec, s[16:17]
	s_cbranch_vccnz .LBB1_35
	v_readlane_b32 s52, v253, 26
	s_lshl_b64 s[16:17], s[14:15], 24
	v_readlane_b32 s66, v253, 40
	v_readlane_b32 s67, v253, 41
	s_add_u32 s16, s66, s16
	s_addc_u32 s17, s67, s17
	s_add_i32 s51, s49, 0xa000
	s_and_b32 s51, s51, 0xffc0
	s_lshl_b32 s50, s50, 2
	s_add_u32 s16, s16, s50
	v_or_b32_e32 v5, s51, v6
	s_addc_u32 s17, s17, 0
	v_lshl_add_u64 v[30:31], s[16:17], 0, v[2:3]
	v_lshlrev_b32_e32 v32, 13, v5
	v_mov_b32_e32 v33, v3
	v_lshl_add_u64 v[58:59], v[30:31], 0, v[32:33]
	v_add_co_u32_e32 v34, vcc, s31, v58
	s_lshl_b32 s16, s51, 1
	s_nop 0
	v_addc_co_u32_e32 v35, vcc, 0, v59, vcc
	v_add_co_u32_e32 v38, vcc, s34, v58
	global_load_dwordx4 v[30:33], v[58:59], off nt
	s_nop 0
	global_load_dwordx4 v[34:37], v[34:35], off nt
	v_addc_co_u32_e32 v39, vcc, 0, v59, vcc
	v_add_co_u32_e32 v42, vcc, s35, v58
	s_add_u32 s16, s47, s16
	s_nop 0
	v_addc_co_u32_e32 v43, vcc, 0, v59, vcc
	v_add_co_u32_e32 v46, vcc, s36, v58
	global_load_dwordx4 v[38:41], v[38:39], off nt
	s_nop 0
	global_load_dwordx4 v[42:45], v[42:43], off nt
	v_addc_co_u32_e32 v47, vcc, 0, v59, vcc
	v_add_co_u32_e32 v50, vcc, s37, v58
	v_mov_b32_e32 v5, v3
	s_nop 0
	v_addc_co_u32_e32 v51, vcc, 0, v59, vcc
	global_load_dwordx4 v[46:49], v[46:47], off nt
	s_nop 0
	global_load_dwordx4 v[50:53], v[50:51], off nt
	v_add_co_u32_e32 v54, vcc, s38, v58
	s_addc_u32 s17, s48, 0
	s_nop 0
	v_addc_co_u32_e32 v55, vcc, 0, v59, vcc
	global_load_dwordx4 v[54:57], v[54:55], off nt
	v_add_co_u32_e32 v58, vcc, s39, v58
	v_lshl_add_u64 v[64:65], s[16:17], 0, v[4:5]
	s_nop 0
	v_addc_co_u32_e32 v59, vcc, 0, v59, vcc
	global_load_dwordx4 v[58:61], v[58:59], off nt
	v_lshlrev_b32_e32 v62, 12, v29
	v_mov_b32_e32 v63, v3
	v_lshlrev_b32_e32 v28, 12, v28
	v_mov_b32_e32 v29, v3
	v_lshl_add_u64 v[64:65], v[64:65], 0, s[4:5]
	v_lshl_add_u64 v[62:63], v[64:65], 0, v[62:63]
	v_lshl_add_u64 v[66:67], v[64:65], 0, v[28:29]
	v_lshlrev_b32_e32 v26, 12, v26
	v_readlane_b32 s53, v253, 27
	v_readlane_b32 s54, v253, 28
	v_readlane_b32 s55, v253, 29
	v_readlane_b32 s56, v253, 30
	v_readlane_b32 s57, v253, 31
	v_readlane_b32 s58, v253, 32
	v_readlane_b32 s59, v253, 33
	v_readlane_b32 s60, v253, 34
	v_readlane_b32 s61, v253, 35
	v_readlane_b32 s62, v253, 36
	v_readlane_b32 s63, v253, 37
	v_readlane_b32 s64, v253, 38
	v_readlane_b32 s65, v253, 39
	s_waitcnt vmcnt(7)
	ds_write2_b32 v11, v30, v31 offset1:1
	ds_write2_b32 v11, v32, v33 offset0:2 offset1:3
	s_waitcnt vmcnt(6)
	ds_write2_b32 v12, v34, v35 offset1:1
	ds_write2_b32 v13, v36, v37 offset1:1
	s_waitcnt vmcnt(5)
	ds_write2_b32 v14, v38, v39 offset1:1
	ds_write2_b32 v15, v40, v41 offset1:1
	s_waitcnt vmcnt(4)
	ds_write2_b32 v16, v42, v43 offset1:1
	ds_write2_b32 v17, v44, v45 offset1:1
	s_waitcnt vmcnt(3)
	ds_write2_b32 v18, v46, v47 offset1:1
	ds_write2_b32 v19, v48, v49 offset1:1
	s_waitcnt vmcnt(2)
	ds_write2_b32 v20, v50, v51 offset1:1
	ds_write2_b32 v21, v52, v53 offset1:1
	s_waitcnt vmcnt(1)
	ds_write2_b32 v22, v54, v55 offset1:1
	ds_write2_b32 v23, v56, v57 offset1:1
	s_waitcnt vmcnt(0)
	ds_write2_b32 v24, v58, v59 offset1:1
	ds_write2_b32 v25, v60, v61 offset1:1
	s_waitcnt lgkmcnt(0)
	ds_read2_b32 v[32:33], v10 offset0:33 offset1:41
	ds_read2_b32 v[34:35], v10 offset1:8
	ds_read2_b32 v[36:37], v10 offset0:66 offset1:74
	ds_read2_b32 v[38:39], v10 offset0:99 offset1:107
	ds_read2_b32 v[40:41], v10 offset0:132 offset1:140
	ds_read2_b32 v[42:43], v10 offset0:165 offset1:173
	ds_read2_b32 v[44:45], v10 offset0:198 offset1:206
	ds_read2_b32 v[46:47], v10 offset0:231 offset1:239
	ds_read2_b32 v[48:49], v10 offset0:49 offset1:57
	ds_read2_b32 v[50:51], v10 offset0:16 offset1:24
	ds_read2_b32 v[52:53], v10 offset0:82 offset1:90
	s_waitcnt lgkmcnt(9)
	v_cvt_pk_bf16_f32 v28, v34, v32
	s_waitcnt lgkmcnt(7)
	v_cvt_pk_bf16_f32 v29, v36, v38
	s_waitcnt lgkmcnt(5)
	v_cvt_pk_bf16_f32 v30, v40, v42
	s_waitcnt lgkmcnt(3)
	v_cvt_pk_bf16_f32 v31, v44, v46
	global_store_dwordx4 v[62:63], v[28:31], off
	v_cvt_pk_bf16_f32 v32, v35, v33
	v_cvt_pk_bf16_f32 v33, v37, v39
	v_cvt_pk_bf16_f32 v34, v41, v43
	v_cvt_pk_bf16_f32 v35, v45, v47
	ds_read2_b32 v[36:37], v10 offset0:115 offset1:123
	ds_read2_b32 v[38:39], v10 offset0:148 offset1:156
	ds_read2_b32 v[40:41], v10 offset0:181 offset1:189
	ds_read2_b32 v[42:43], v10 offset0:214 offset1:222
	ds_read2_b32 v[44:45], v10 offset0:247 offset1:255
	global_store_dwordx4 v[66:67], v[32:35], off
	s_waitcnt lgkmcnt(6)
	v_cvt_pk_bf16_f32 v28, v50, v48
	s_waitcnt lgkmcnt(4)
	v_cvt_pk_bf16_f32 v29, v52, v36
	v_lshlrev_b32_e32 v32, 12, v27
	v_mov_b32_e32 v33, v3
	s_waitcnt lgkmcnt(2)
	v_cvt_pk_bf16_f32 v30, v38, v40
	s_waitcnt lgkmcnt(0)
	v_cvt_pk_bf16_f32 v31, v42, v44
	v_lshl_add_u64 v[32:33], v[64:65], 0, v[32:33]
	v_mov_b32_e32 v27, v3
	global_store_dwordx4 v[32:33], v[28:31], off
	v_lshl_add_u64 v[26:27], v[64:65], 0, v[26:27]
	s_nop 0
	v_cvt_pk_bf16_f32 v28, v51, v49
	v_cvt_pk_bf16_f32 v29, v53, v37
	v_cvt_pk_bf16_f32 v30, v39, v41
	v_cvt_pk_bf16_f32 v31, v43, v45
	global_store_dwordx4 v[26:27], v[28:31], off
	s_waitcnt lgkmcnt(0)

.LBB1_36:
	s_andn2_b64 vcc, exec, s[16:17]
	s_cbranch_vccnz .LBB1_38
	v_readlane_b32 s52, v253, 26
	s_lshl_b64 s[16:17], s[14:15], 23
	v_readlane_b32 s64, v253, 38
	v_readlane_b32 s65, v253, 39
	s_add_u32 s16, s64, s16
	s_addc_u32 s17, s65, s17
	s_add_i32 s50, s49, 0xa400
	s_and_b32 s51, s29, 0x7e0
	s_and_b32 s50, s50, 0xffc0
	s_lshl_b32 s52, s51, 2
	s_add_u32 s16, s16, s52
	v_or_b32_e32 v5, s50, v6
	s_addc_u32 s17, s17, 0
	v_lshl_add_u64 v[26:27], s[16:17], 0, v[2:3]
	v_lshlrev_b32_e32 v28, 13, v5
	v_mov_b32_e32 v29, v3
	v_lshl_add_u64 v[54:55], v[26:27], 0, v[28:29]
	v_add_co_u32_e32 v30, vcc, s31, v54
	s_lshl_b32 s16, s50, 1
	s_nop 0
	v_addc_co_u32_e32 v31, vcc, 0, v55, vcc
	v_add_co_u32_e32 v34, vcc, s34, v54
	global_load_dwordx4 v[26:29], v[54:55], off nt
	s_nop 0
	global_load_dwordx4 v[30:33], v[30:31], off nt
	v_addc_co_u32_e32 v35, vcc, 0, v55, vcc
	v_add_co_u32_e32 v38, vcc, s35, v54
	s_add_u32 s16, s47, s16
	s_nop 0
	v_addc_co_u32_e32 v39, vcc, 0, v55, vcc
	v_add_co_u32_e32 v42, vcc, s36, v54
	global_load_dwordx4 v[34:37], v[34:35], off nt
	s_nop 0
	global_load_dwordx4 v[38:41], v[38:39], off nt
	v_addc_co_u32_e32 v43, vcc, 0, v55, vcc
	v_add_co_u32_e32 v46, vcc, s37, v54
	v_mov_b32_e32 v5, v3
	s_nop 0
	v_addc_co_u32_e32 v47, vcc, 0, v55, vcc
	global_load_dwordx4 v[42:45], v[42:43], off nt
	s_nop 0
	global_load_dwordx4 v[46:49], v[46:47], off nt
	v_add_co_u32_e32 v50, vcc, s38, v54
	s_addc_u32 s17, s48, 0
	s_nop 0
	v_addc_co_u32_e32 v51, vcc, 0, v55, vcc
	global_load_dwordx4 v[50:53], v[50:51], off nt
	v_add_co_u32_e32 v54, vcc, s39, v54
	v_or_b32_e32 v58, s51, v6
	s_nop 0
	v_addc_co_u32_e32 v55, vcc, 0, v55, vcc
	global_load_dwordx4 v[54:57], v[54:55], off nt
	v_lshl_add_u64 v[62:63], s[16:17], 0, v[4:5]
	v_mov_b32_e32 v59, v3
	v_lshlrev_b32_e32 v58, 12, v58
	v_lshl_add_u64 v[62:63], v[62:63], 0, s[6:7]
	v_lshl_add_u64 v[58:59], v[62:63], 0, v[58:59]
	v_or_b32_e32 v60, s51, v7
	v_mov_b32_e32 v61, v3
	v_lshlrev_b32_e32 v60, 12, v60
	v_or_b32_e32 v5, s51, v8
	v_readlane_b32 s53, v253, 27
	v_readlane_b32 s54, v253, 28
	v_readlane_b32 s55, v253, 29
	v_readlane_b32 s56, v253, 30
	v_readlane_b32 s57, v253, 31
	v_readlane_b32 s58, v253, 32
	v_readlane_b32 s59, v253, 33
	v_readlane_b32 s60, v253, 34
	v_readlane_b32 s61, v253, 35
	v_readlane_b32 s62, v253, 36
	v_readlane_b32 s63, v253, 37
	v_readlane_b32 s66, v253, 40
	v_readlane_b32 s67, v253, 41
	s_waitcnt vmcnt(7)
	ds_write2_b32 v11, v26, v27 offset1:1
	ds_write2_b32 v11, v28, v29 offset0:2 offset1:3
	s_waitcnt vmcnt(6)
	ds_write2_b32 v12, v30, v31 offset1:1
	ds_write2_b32 v13, v32, v33 offset1:1
	s_waitcnt vmcnt(5)
	ds_write2_b32 v14, v34, v35 offset1:1
	ds_write2_b32 v15, v36, v37 offset1:1
	s_waitcnt vmcnt(4)
	ds_write2_b32 v16, v38, v39 offset1:1
	ds_write2_b32 v17, v40, v41 offset1:1
	s_waitcnt vmcnt(3)
	ds_write2_b32 v18, v42, v43 offset1:1
	ds_write2_b32 v19, v44, v45 offset1:1
	s_waitcnt vmcnt(2)
	ds_write2_b32 v20, v46, v47 offset1:1
	ds_write2_b32 v21, v48, v49 offset1:1
	s_waitcnt vmcnt(1)
	ds_write2_b32 v22, v50, v51 offset1:1
	ds_write2_b32 v23, v52, v53 offset1:1
	s_waitcnt vmcnt(0)
	ds_write2_b32 v24, v54, v55 offset1:1
	ds_write2_b32 v25, v56, v57 offset1:1
	s_waitcnt lgkmcnt(0)
	ds_read2_b32 v[30:31], v10 offset0:33 offset1:41
	ds_read2_b32 v[32:33], v10 offset1:8
	ds_read2_b32 v[34:35], v10 offset0:66 offset1:74
	ds_read2_b32 v[36:37], v10 offset0:99 offset1:107
	ds_read2_b32 v[38:39], v10 offset0:132 offset1:140
	ds_read2_b32 v[40:41], v10 offset0:165 offset1:173
	ds_read2_b32 v[42:43], v10 offset0:198 offset1:206
	ds_read2_b32 v[44:45], v10 offset0:231 offset1:239
	s_waitcnt lgkmcnt(6)
	v_cvt_pk_bf16_f32 v26, v32, v30
	s_waitcnt lgkmcnt(4)
	v_cvt_pk_bf16_f32 v27, v34, v36
	s_waitcnt lgkmcnt(2)
	v_cvt_pk_bf16_f32 v28, v38, v40
	v_cvt_pk_bf16_f32 v30, v33, v31
	s_waitcnt lgkmcnt(0)
	v_cvt_pk_bf16_f32 v29, v42, v44
	global_store_dwordx4 v[58:59], v[26:29], off
	v_cvt_pk_bf16_f32 v31, v35, v37
	v_cvt_pk_bf16_f32 v32, v39, v41
	v_cvt_pk_bf16_f32 v33, v43, v45
	ds_read2_b32 v[34:35], v10 offset0:49 offset1:57
	ds_read2_b32 v[36:37], v10 offset0:16 offset1:24
	ds_read2_b32 v[38:39], v10 offset0:82 offset1:90
	ds_read2_b32 v[40:41], v10 offset0:115 offset1:123
	ds_read2_b32 v[42:43], v10 offset0:148 offset1:156
	ds_read2_b32 v[44:45], v10 offset0:181 offset1:189
	ds_read2_b32 v[48:49], v10 offset0:214 offset1:222
	ds_read2_b32 v[50:51], v10 offset0:247 offset1:255
	v_lshl_add_u64 v[46:47], v[62:63], 0, v[60:61]
	global_store_dwordx4 v[46:47], v[30:33], off
	s_waitcnt lgkmcnt(6)
	v_cvt_pk_bf16_f32 v26, v36, v34
	s_waitcnt lgkmcnt(4)
	v_cvt_pk_bf16_f32 v27, v38, v40
	v_lshlrev_b32_e32 v30, 12, v5
	v_mov_b32_e32 v31, v3
	s_waitcnt lgkmcnt(2)
	v_cvt_pk_bf16_f32 v28, v42, v44
	s_waitcnt lgkmcnt(0)
	v_cvt_pk_bf16_f32 v29, v48, v50
	v_lshl_add_u64 v[30:31], v[62:63], 0, v[30:31]
	v_or_b32_e32 v5, s51, v9
	global_store_dwordx4 v[30:31], v[26:29], off
	v_lshlrev_b32_e32 v30, 12, v5
	v_mov_b32_e32 v31, v3
	v_cvt_pk_bf16_f32 v26, v37, v35
	v_cvt_pk_bf16_f32 v27, v39, v41
	v_cvt_pk_bf16_f32 v28, v43, v45
	v_cvt_pk_bf16_f32 v29, v49, v51
	v_lshl_add_u64 v[30:31], v[62:63], 0, v[30:31]
	global_store_dwordx4 v[30:31], v[26:29], off
	s_waitcnt lgkmcnt(0)

.LBB1_39:
	s_andn2_b64 vcc, exec, s[16:17]
	s_cbranch_vccnz .LBB1_41
	v_readlane_b32 s52, v253, 26
	s_lshl_b64 s[16:17], s[14:15], 22
	v_readlane_b32 s62, v253, 36
	v_readlane_b32 s63, v253, 37
	s_add_u32 s16, s62, s16
	s_addc_u32 s17, s63, s17
	s_add_i32 s50, s49, 0xa600
	s_and_b32 s51, s29, 0x7e0
	s_and_b32 s50, s50, 0xffc0
	s_lshl_b32 s52, s51, 2
	s_add_u32 s16, s16, s52
	v_or_b32_e32 v5, s50, v6
	s_addc_u32 s17, s17, 0
	v_lshl_add_u64 v[26:27], s[16:17], 0, v[2:3]
	v_lshlrev_b32_e32 v28, 13, v5
	v_mov_b32_e32 v29, v3
	v_lshl_add_u64 v[54:55], v[26:27], 0, v[28:29]
	v_add_co_u32_e32 v30, vcc, s31, v54
	s_lshl_b32 s16, s50, 1
	s_nop 0
	v_addc_co_u32_e32 v31, vcc, 0, v55, vcc
	v_add_co_u32_e32 v34, vcc, s34, v54
	global_load_dwordx4 v[26:29], v[54:55], off nt
	s_nop 0
	global_load_dwordx4 v[30:33], v[30:31], off nt
	v_addc_co_u32_e32 v35, vcc, 0, v55, vcc
	v_add_co_u32_e32 v38, vcc, s35, v54
	s_add_u32 s16, s47, s16
	s_nop 0
	v_addc_co_u32_e32 v39, vcc, 0, v55, vcc
	v_add_co_u32_e32 v42, vcc, s36, v54
	global_load_dwordx4 v[34:37], v[34:35], off nt
	s_nop 0
	global_load_dwordx4 v[38:41], v[38:39], off nt
	v_addc_co_u32_e32 v43, vcc, 0, v55, vcc
	v_add_co_u32_e32 v46, vcc, s37, v54
	v_mov_b32_e32 v5, v3
	s_nop 0
	v_addc_co_u32_e32 v47, vcc, 0, v55, vcc
	global_load_dwordx4 v[42:45], v[42:43], off nt
	s_nop 0
	global_load_dwordx4 v[46:49], v[46:47], off nt
	v_add_co_u32_e32 v50, vcc, s38, v54
	s_addc_u32 s17, s48, 0
	s_nop 0
	v_addc_co_u32_e32 v51, vcc, 0, v55, vcc
	global_load_dwordx4 v[50:53], v[50:51], off nt
	v_add_co_u32_e32 v54, vcc, s39, v54
	v_or_b32_e32 v58, s51, v6
	s_nop 0
	v_addc_co_u32_e32 v55, vcc, 0, v55, vcc
	global_load_dwordx4 v[54:57], v[54:55], off nt
	v_lshl_add_u64 v[62:63], s[16:17], 0, v[4:5]
	v_mov_b32_e32 v59, v3
	v_lshlrev_b32_e32 v58, 12, v58
	v_lshl_add_u64 v[62:63], v[62:63], 0, s[8:9]
	v_lshl_add_u64 v[58:59], v[62:63], 0, v[58:59]
	v_or_b32_e32 v60, s51, v7
	v_mov_b32_e32 v61, v3
	v_lshlrev_b32_e32 v60, 12, v60
	v_or_b32_e32 v5, s51, v8
	v_readlane_b32 s53, v253, 27
	v_readlane_b32 s54, v253, 28
	v_readlane_b32 s55, v253, 29
	v_readlane_b32 s56, v253, 30
	v_readlane_b32 s57, v253, 31
	v_readlane_b32 s58, v253, 32
	v_readlane_b32 s59, v253, 33
	v_readlane_b32 s60, v253, 34
	v_readlane_b32 s61, v253, 35
	v_readlane_b32 s64, v253, 38
	v_readlane_b32 s65, v253, 39
	v_readlane_b32 s66, v253, 40
	v_readlane_b32 s67, v253, 41
	s_waitcnt vmcnt(7)
	ds_write2_b32 v11, v26, v27 offset1:1
	ds_write2_b32 v11, v28, v29 offset0:2 offset1:3
	s_waitcnt vmcnt(6)
	ds_write2_b32 v12, v30, v31 offset1:1
	ds_write2_b32 v13, v32, v33 offset1:1
	s_waitcnt vmcnt(5)
	ds_write2_b32 v14, v34, v35 offset1:1
	ds_write2_b32 v15, v36, v37 offset1:1
	s_waitcnt vmcnt(4)
	ds_write2_b32 v16, v38, v39 offset1:1
	ds_write2_b32 v17, v40, v41 offset1:1
	s_waitcnt vmcnt(3)
	ds_write2_b32 v18, v42, v43 offset1:1
	ds_write2_b32 v19, v44, v45 offset1:1
	s_waitcnt vmcnt(2)
	ds_write2_b32 v20, v46, v47 offset1:1
	ds_write2_b32 v21, v48, v49 offset1:1
	s_waitcnt vmcnt(1)
	ds_write2_b32 v22, v50, v51 offset1:1
	ds_write2_b32 v23, v52, v53 offset1:1
	s_waitcnt vmcnt(0)
	ds_write2_b32 v24, v54, v55 offset1:1
	ds_write2_b32 v25, v56, v57 offset1:1
	s_waitcnt lgkmcnt(0)
	ds_read2_b32 v[30:31], v10 offset0:33 offset1:41
	ds_read2_b32 v[32:33], v10 offset1:8
	ds_read2_b32 v[34:35], v10 offset0:66 offset1:74
	ds_read2_b32 v[36:37], v10 offset0:99 offset1:107
	ds_read2_b32 v[38:39], v10 offset0:132 offset1:140
	ds_read2_b32 v[40:41], v10 offset0:165 offset1:173
	ds_read2_b32 v[42:43], v10 offset0:198 offset1:206
	ds_read2_b32 v[44:45], v10 offset0:231 offset1:239
	s_waitcnt lgkmcnt(6)
	v_cvt_pk_bf16_f32 v26, v32, v30
	s_waitcnt lgkmcnt(4)
	v_cvt_pk_bf16_f32 v27, v34, v36
	s_waitcnt lgkmcnt(2)
	v_cvt_pk_bf16_f32 v28, v38, v40
	v_cvt_pk_bf16_f32 v30, v33, v31
	s_waitcnt lgkmcnt(0)
	v_cvt_pk_bf16_f32 v29, v42, v44
	global_store_dwordx4 v[58:59], v[26:29], off
	v_cvt_pk_bf16_f32 v31, v35, v37
	v_cvt_pk_bf16_f32 v32, v39, v41
	v_cvt_pk_bf16_f32 v33, v43, v45
	ds_read2_b32 v[34:35], v10 offset0:49 offset1:57
	ds_read2_b32 v[36:37], v10 offset0:16 offset1:24
	ds_read2_b32 v[38:39], v10 offset0:82 offset1:90
	ds_read2_b32 v[40:41], v10 offset0:115 offset1:123
	ds_read2_b32 v[42:43], v10 offset0:148 offset1:156
	ds_read2_b32 v[44:45], v10 offset0:181 offset1:189
	ds_read2_b32 v[48:49], v10 offset0:214 offset1:222
	ds_read2_b32 v[50:51], v10 offset0:247 offset1:255
	v_lshl_add_u64 v[46:47], v[62:63], 0, v[60:61]
	global_store_dwordx4 v[46:47], v[30:33], off
	s_waitcnt lgkmcnt(6)
	v_cvt_pk_bf16_f32 v26, v36, v34
	s_waitcnt lgkmcnt(4)
	v_cvt_pk_bf16_f32 v27, v38, v40
	v_lshlrev_b32_e32 v30, 12, v5
	v_mov_b32_e32 v31, v3
	s_waitcnt lgkmcnt(2)
	v_cvt_pk_bf16_f32 v28, v42, v44
	s_waitcnt lgkmcnt(0)
	v_cvt_pk_bf16_f32 v29, v48, v50
	v_lshl_add_u64 v[30:31], v[62:63], 0, v[30:31]
	v_or_b32_e32 v5, s51, v9
	global_store_dwordx4 v[30:31], v[26:29], off
	v_lshlrev_b32_e32 v30, 12, v5
	v_mov_b32_e32 v31, v3
	v_cvt_pk_bf16_f32 v26, v37, v35
	v_cvt_pk_bf16_f32 v27, v39, v41
	v_cvt_pk_bf16_f32 v28, v43, v45
	v_cvt_pk_bf16_f32 v29, v49, v51
	v_lshl_add_u64 v[30:31], v[62:63], 0, v[30:31]
	global_store_dwordx4 v[30:31], v[26:29], off
	s_waitcnt lgkmcnt(0)

.LBB1_42:
	s_andn2_b64 vcc, exec, s[16:17]
	s_cbranch_vccnz .LBB1_44
	v_readlane_b32 s52, v253, 26
	s_lshl_b64 s[16:17], s[14:15], 22
	v_readlane_b32 s60, v253, 34
	v_readlane_b32 s61, v253, 35
	s_add_u32 s15, s60, s16
	s_addc_u32 s17, s61, s17
	s_add_i32 s16, s49, 0xa800
	s_and_b32 s51, s29, 0x7e0
	s_and_b32 s50, s16, 0xffc0
	s_lshl_b32 s16, s51, 2
	s_add_u32 s16, s15, s16
	v_or_b32_e32 v5, s50, v6
	s_addc_u32 s17, s17, 0
	v_lshl_add_u64 v[26:27], s[16:17], 0, v[2:3]
	v_lshlrev_b32_e32 v28, 13, v5
	v_mov_b32_e32 v29, v3
	v_lshl_add_u64 v[54:55], v[26:27], 0, v[28:29]
	v_add_co_u32_e32 v30, vcc, s31, v54
	s_lshl_b32 s15, s50, 1
	s_nop 0
	v_addc_co_u32_e32 v31, vcc, 0, v55, vcc
	v_add_co_u32_e32 v34, vcc, s34, v54
	global_load_dwordx4 v[26:29], v[54:55], off nt
	s_nop 0
	global_load_dwordx4 v[30:33], v[30:31], off nt
	v_addc_co_u32_e32 v35, vcc, 0, v55, vcc
	v_add_co_u32_e32 v38, vcc, s35, v54
	s_add_u32 s16, s47, s15
	s_nop 0
	v_addc_co_u32_e32 v39, vcc, 0, v55, vcc
	v_add_co_u32_e32 v42, vcc, s36, v54
	global_load_dwordx4 v[34:37], v[34:35], off nt
	s_nop 0
	global_load_dwordx4 v[38:41], v[38:39], off nt
	v_addc_co_u32_e32 v43, vcc, 0, v55, vcc
	v_add_co_u32_e32 v46, vcc, s37, v54
	v_mov_b32_e32 v5, v3
	s_nop 0
	v_addc_co_u32_e32 v47, vcc, 0, v55, vcc
	global_load_dwordx4 v[42:45], v[42:43], off nt
	s_nop 0
	global_load_dwordx4 v[46:49], v[46:47], off nt
	v_add_co_u32_e32 v50, vcc, s38, v54
	s_addc_u32 s17, s48, 0
	s_nop 0
	v_addc_co_u32_e32 v51, vcc, 0, v55, vcc
	global_load_dwordx4 v[50:53], v[50:51], off nt
	v_add_co_u32_e32 v54, vcc, s39, v54
	v_or_b32_e32 v58, s51, v6
	s_nop 0
	v_addc_co_u32_e32 v55, vcc, 0, v55, vcc
	global_load_dwordx4 v[54:57], v[54:55], off nt
	v_lshl_add_u64 v[62:63], s[16:17], 0, v[4:5]
	v_mov_b32_e32 v59, v3
	v_lshlrev_b32_e32 v58, 12, v58
	v_lshl_add_u64 v[62:63], v[62:63], 0, s[10:11]
	v_lshl_add_u64 v[58:59], v[62:63], 0, v[58:59]
	v_or_b32_e32 v60, s51, v7
	v_mov_b32_e32 v61, v3
	v_lshlrev_b32_e32 v60, 12, v60
	v_or_b32_e32 v5, s51, v8
	v_readlane_b32 s53, v253, 27
	v_readlane_b32 s54, v253, 28
	v_readlane_b32 s55, v253, 29
	v_readlane_b32 s56, v253, 30
	v_readlane_b32 s57, v253, 31
	v_readlane_b32 s58, v253, 32
	v_readlane_b32 s59, v253, 33
	v_readlane_b32 s62, v253, 36
	v_readlane_b32 s63, v253, 37
	v_readlane_b32 s64, v253, 38
	v_readlane_b32 s65, v253, 39
	v_readlane_b32 s66, v253, 40
	v_readlane_b32 s67, v253, 41
	s_waitcnt vmcnt(7)
	ds_write2_b32 v11, v26, v27 offset1:1
	ds_write2_b32 v11, v28, v29 offset0:2 offset1:3
	s_waitcnt vmcnt(6)
	ds_write2_b32 v12, v30, v31 offset1:1
	ds_write2_b32 v13, v32, v33 offset1:1
	s_waitcnt vmcnt(5)
	ds_write2_b32 v14, v34, v35 offset1:1
	ds_write2_b32 v15, v36, v37 offset1:1
	s_waitcnt vmcnt(4)
	ds_write2_b32 v16, v38, v39 offset1:1
	ds_write2_b32 v17, v40, v41 offset1:1
	s_waitcnt vmcnt(3)
	ds_write2_b32 v18, v42, v43 offset1:1
	ds_write2_b32 v19, v44, v45 offset1:1
	s_waitcnt vmcnt(2)
	ds_write2_b32 v20, v46, v47 offset1:1
	ds_write2_b32 v21, v48, v49 offset1:1
	s_waitcnt vmcnt(1)
	ds_write2_b32 v22, v50, v51 offset1:1
	ds_write2_b32 v23, v52, v53 offset1:1
	s_waitcnt vmcnt(0)
	ds_write2_b32 v24, v54, v55 offset1:1
	ds_write2_b32 v25, v56, v57 offset1:1
	s_waitcnt lgkmcnt(0)
	ds_read2_b32 v[30:31], v10 offset0:33 offset1:41
	ds_read2_b32 v[32:33], v10 offset1:8
	ds_read2_b32 v[34:35], v10 offset0:66 offset1:74
	ds_read2_b32 v[36:37], v10 offset0:99 offset1:107
	ds_read2_b32 v[38:39], v10 offset0:132 offset1:140
	ds_read2_b32 v[40:41], v10 offset0:165 offset1:173
	ds_read2_b32 v[42:43], v10 offset0:198 offset1:206
	ds_read2_b32 v[44:45], v10 offset0:231 offset1:239
	s_waitcnt lgkmcnt(6)
	v_cvt_pk_bf16_f32 v26, v32, v30
	s_waitcnt lgkmcnt(4)
	v_cvt_pk_bf16_f32 v27, v34, v36
	s_waitcnt lgkmcnt(2)
	v_cvt_pk_bf16_f32 v28, v38, v40
	v_cvt_pk_bf16_f32 v30, v33, v31
	s_waitcnt lgkmcnt(0)
	v_cvt_pk_bf16_f32 v29, v42, v44
	global_store_dwordx4 v[58:59], v[26:29], off
	v_cvt_pk_bf16_f32 v31, v35, v37
	v_cvt_pk_bf16_f32 v32, v39, v41
	v_cvt_pk_bf16_f32 v33, v43, v45
	ds_read2_b32 v[34:35], v10 offset0:49 offset1:57
	ds_read2_b32 v[36:37], v10 offset0:16 offset1:24
	ds_read2_b32 v[38:39], v10 offset0:82 offset1:90
	ds_read2_b32 v[40:41], v10 offset0:115 offset1:123
	ds_read2_b32 v[42:43], v10 offset0:148 offset1:156
	ds_read2_b32 v[44:45], v10 offset0:181 offset1:189
	ds_read2_b32 v[48:49], v10 offset0:214 offset1:222
	ds_read2_b32 v[50:51], v10 offset0:247 offset1:255
	v_lshl_add_u64 v[46:47], v[62:63], 0, v[60:61]
	global_store_dwordx4 v[46:47], v[30:33], off
	s_waitcnt lgkmcnt(6)
	v_cvt_pk_bf16_f32 v26, v36, v34
	s_waitcnt lgkmcnt(4)
	v_cvt_pk_bf16_f32 v27, v38, v40
	v_lshlrev_b32_e32 v30, 12, v5
	v_mov_b32_e32 v31, v3
	s_waitcnt lgkmcnt(2)
	v_cvt_pk_bf16_f32 v28, v42, v44
	s_waitcnt lgkmcnt(0)
	v_cvt_pk_bf16_f32 v29, v48, v50
	v_lshl_add_u64 v[30:31], v[62:63], 0, v[30:31]
	v_or_b32_e32 v5, s51, v9
	global_store_dwordx4 v[30:31], v[26:29], off
	v_lshlrev_b32_e32 v30, 12, v5
	v_mov_b32_e32 v31, v3
	v_cvt_pk_bf16_f32 v26, v37, v35
	v_cvt_pk_bf16_f32 v27, v39, v41
	v_cvt_pk_bf16_f32 v28, v43, v45
	v_cvt_pk_bf16_f32 v29, v49, v51
	v_lshl_add_u64 v[30:31], v[62:63], 0, v[30:31]
	global_store_dwordx4 v[30:31], v[26:29], off
	s_waitcnt lgkmcnt(0)

.LBB1_45:
	s_andn2_b64 vcc, exec, s[16:17]
	s_cbranch_vccnz .LBB1_47
	s_mul_i32 s16, s14, 0x5800000
	v_readlane_b32 s52, v253, 0
	s_mul_hi_i32 s15, s14, 0x5800000
	v_readlane_b32 s53, v253, 1
	s_add_u32 s16, s52, s16
	s_addc_u32 s15, s53, s15
	s_add_i32 s17, s49, 0xd400
	s_and_b32 s50, s17, 0xffff
	s_mul_i32 s50, s50, 0xba2f
	s_lshr_b32 s50, s50, 24
	s_mul_i32 s51, s50, 0x160
	s_sub_i32 s17, s17, s51
	s_and_b32 s51, s17, 0xffff
	s_lshl_b32 s52, s51, 5
	s_lshl_b32 s17, s51, 7
	v_lshl_or_b32 v5, s50, 6, v6
	s_add_u32 s16, s16, s17
	s_addc_u32 s17, s15, 0
	v_mul_u32_u24_e32 v5, 0x2c00, v5
	v_lshl_add_u64 v[26:27], s[16:17], 0, v[2:3]
	v_lshlrev_b32_e32 v28, 2, v5
	v_mov_b32_e32 v29, v3
	v_lshl_add_u64 v[54:55], v[26:27], 0, v[28:29]
	v_add_co_u32_e32 v30, vcc, s40, v54
	s_lshl_b32 s15, s51, 6
	s_nop 0
	v_addc_co_u32_e32 v31, vcc, 0, v55, vcc
	v_add_co_u32_e32 v34, vcc, s41, v54
	global_load_dwordx4 v[26:29], v[54:55], off nt
	s_nop 0
	global_load_dwordx4 v[30:33], v[30:31], off nt
	v_addc_co_u32_e32 v35, vcc, 0, v55, vcc
	v_add_co_u32_e32 v38, vcc, s42, v54
	s_lshl_b32 s16, s50, 7
	s_nop 0
	v_addc_co_u32_e32 v39, vcc, 0, v55, vcc
	v_add_co_u32_e32 v42, vcc, s43, v54
	global_load_dwordx4 v[34:37], v[34:35], off nt
	s_nop 0
	global_load_dwordx4 v[38:41], v[38:39], off nt
	v_addc_co_u32_e32 v43, vcc, 0, v55, vcc
	v_add_co_u32_e32 v46, vcc, s44, v54
	s_and_b32 s15, s15, 0xc0
	s_nop 0
	v_addc_co_u32_e32 v47, vcc, 0, v55, vcc
	global_load_dwordx4 v[42:45], v[42:43], off nt
	s_nop 0
	global_load_dwordx4 v[46:49], v[46:47], off nt
	v_add_co_u32_e32 v50, vcc, s45, v54
	s_add_u32 s16, s47, s16
	s_nop 0
	v_addc_co_u32_e32 v51, vcc, 0, v55, vcc
	global_load_dwordx4 v[50:53], v[50:51], off nt
	v_add_co_u32_e32 v54, vcc, s46, v54
	s_addc_u32 s17, s48, 0
	s_nop 0
	v_addc_co_u32_e32 v55, vcc, 0, v55, vcc
	global_load_dwordx4 v[54:57], v[54:55], off nt
	v_mov_b32_e32 v5, v3
	s_cmpk_gt_u32 s51, 0xaf
	v_lshl_add_u64 v[58:59], s[16:17], 0, v[4:5]
	s_cselect_b32 s16, 0xffffea00, 0
	s_cselect_b32 s17, 32, 0
	s_add_i32 s52, s52, s16
	s_lshl_b32 s16, s52, 1
	s_or_b32 s15, s15, s17
	s_and_b32 s16, s16, 0xffffff00
	s_or_b32 s15, s15, s16
	v_lshl_add_u64 v[58:59], v[58:59], 0, s[12:13]
	v_readlane_b32 s56, v253, 4
	v_readlane_b32 s57, v253, 5
	v_readlane_b32 s58, v253, 6
	v_readlane_b32 s59, v253, 7
	v_readlane_b32 s56, v253, 42
	v_readlane_b32 s57, v253, 43
	v_readlane_b32 s59, v253, 45
	v_readlane_b32 s91, v253, 46
	s_mov_b64 s[76:77], s[56:57]
	s_mov_b32 s79, s59
	v_readlane_b32 s54, v253, 2
	v_readlane_b32 s55, v253, 3
	v_readlane_b32 s58, v253, 44
	s_waitcnt vmcnt(7)
	ds_write2_b32 v11, v26, v27 offset1:1
	ds_write2_b32 v11, v28, v29 offset0:2 offset1:3
	s_waitcnt vmcnt(6)
	ds_write2_b32 v12, v30, v31 offset1:1
	ds_write2_b32 v13, v32, v33 offset1:1
	s_waitcnt vmcnt(5)
	ds_write2_b32 v14, v34, v35 offset1:1
	ds_write2_b32 v15, v36, v37 offset1:1
	s_waitcnt vmcnt(4)
	ds_write2_b32 v16, v38, v39 offset1:1
	ds_write2_b32 v17, v40, v41 offset1:1
	s_waitcnt vmcnt(3)
	ds_write2_b32 v18, v42, v43 offset1:1
	ds_write2_b32 v19, v44, v45 offset1:1
	s_waitcnt vmcnt(2)
	ds_write2_b32 v20, v46, v47 offset1:1
	ds_write2_b32 v21, v48, v49 offset1:1
	s_waitcnt vmcnt(1)
	ds_write2_b32 v22, v50, v51 offset1:1
	ds_write2_b32 v23, v52, v53 offset1:1
	s_waitcnt vmcnt(0)
	ds_write2_b32 v24, v54, v55 offset1:1
	ds_write2_b32 v25, v56, v57 offset1:1
	s_waitcnt lgkmcnt(0)
	ds_read2_b32 v[30:31], v10 offset0:33 offset1:41
	ds_read2_b32 v[32:33], v10 offset1:8
	ds_read2_b32 v[34:35], v10 offset0:66 offset1:74
	ds_read2_b32 v[36:37], v10 offset0:99 offset1:107
	ds_read2_b32 v[38:39], v10 offset0:132 offset1:140
	ds_read2_b32 v[40:41], v10 offset0:165 offset1:173
	ds_read2_b32 v[42:43], v10 offset0:198 offset1:206
	ds_read2_b32 v[44:45], v10 offset0:231 offset1:239
	v_or_b32_e32 v46, s15, v6
	v_ashrrev_i32_e32 v47, 31, v46
	v_lshlrev_b64 v[46:47], 12, v[46:47]
	s_waitcnt lgkmcnt(6)
	v_cvt_pk_bf16_f32 v26, v32, v30
	s_waitcnt lgkmcnt(4)
	v_cvt_pk_bf16_f32 v27, v34, v36
	s_waitcnt lgkmcnt(2)
	v_cvt_pk_bf16_f32 v28, v38, v40
	s_waitcnt lgkmcnt(0)
	v_cvt_pk_bf16_f32 v29, v42, v44
	v_lshl_add_u64 v[46:47], v[58:59], 0, v[46:47]
	v_or_b32_e32 v30, s15, v7
	global_store_dwordx4 v[46:47], v[26:29], off
	s_nop 1
	v_cvt_pk_bf16_f32 v26, v33, v31
	v_ashrrev_i32_e32 v31, 31, v30
	v_cvt_pk_bf16_f32 v27, v35, v37
	v_cvt_pk_bf16_f32 v28, v39, v41
	v_cvt_pk_bf16_f32 v29, v43, v45
	v_lshlrev_b64 v[30:31], 12, v[30:31]
	ds_read2_b32 v[32:33], v10 offset0:49 offset1:57
	ds_read2_b32 v[34:35], v10 offset0:16 offset1:24
	ds_read2_b32 v[36:37], v10 offset0:82 offset1:90
	ds_read2_b32 v[38:39], v10 offset0:115 offset1:123
	ds_read2_b32 v[40:41], v10 offset0:148 offset1:156
	ds_read2_b32 v[42:43], v10 offset0:181 offset1:189
	ds_read2_b32 v[44:45], v10 offset0:214 offset1:222
	ds_read2_b32 v[46:47], v10 offset0:247 offset1:255
	v_lshl_add_u64 v[30:31], v[58:59], 0, v[30:31]
	global_store_dwordx4 v[30:31], v[26:29], off
	v_or_b32_e32 v30, s15, v8
	v_ashrrev_i32_e32 v31, 31, v30
	v_lshlrev_b64 v[30:31], 12, v[30:31]
	s_waitcnt lgkmcnt(6)
	v_cvt_pk_bf16_f32 v26, v34, v32
	s_waitcnt lgkmcnt(4)
	v_cvt_pk_bf16_f32 v27, v36, v38
	s_waitcnt lgkmcnt(2)
	v_cvt_pk_bf16_f32 v28, v40, v42
	s_waitcnt lgkmcnt(0)
	v_cvt_pk_bf16_f32 v29, v44, v46
	v_lshl_add_u64 v[30:31], v[58:59], 0, v[30:31]
	global_store_dwordx4 v[30:31], v[26:29], off
	v_or_b32_e32 v30, s15, v9
	v_ashrrev_i32_e32 v31, 31, v30
	v_lshlrev_b64 v[30:31], 12, v[30:31]
	v_cvt_pk_bf16_f32 v26, v35, v33
	v_cvt_pk_bf16_f32 v27, v37, v39
	v_cvt_pk_bf16_f32 v28, v41, v43
	v_cvt_pk_bf16_f32 v29, v45, v47
	v_lshl_add_u64 v[30:31], v[58:59], 0, v[30:31]
	global_store_dwordx4 v[30:31], v[26:29], off
	s_waitcnt lgkmcnt(0)

.LBB1_49:
	s_mul_hi_i32 s15, s14, 0x5800000
	s_mul_i32 s14, s14, 0x5800000
	v_readlane_b32 s52, v253, 26
	v_readlane_b32 s53, v253, 27
	s_add_u32 s17, s52, s14
	s_mul_i32 s14, s49, 0xba3
	s_addc_u32 s52, s53, s15
	s_lshr_b32 s15, s14, 31
	s_ashr_i32 s14, s14, 20
	s_add_i32 s14, s14, s15
	s_mul_i32 s15, s14, 0x160
	s_sub_i32 s15, s49, s15
	s_sext_i32_i16 s15, s15
	s_lshl_b32 s16, s14, 6
	s_lshl_b32 s14, s15, 5
	s_ashr_i32 s15, s14, 31
	s_lshl_b64 s[50:51], s[14:15], 2
	v_or_b32_e32 v5, s16, v6
	s_add_u32 s50, s17, s50
	s_addc_u32 s51, s52, s51
	v_mul_i32_i24_e32 v28, 0x2c00, v5
	v_lshl_add_u64 v[26:27], s[50:51], 0, v[2:3]
	v_ashrrev_i32_e32 v29, 31, v28
	v_lshl_add_u64 v[54:55], v[28:29], 2, v[26:27]
	v_add_co_u32_e32 v30, vcc, s40, v54
	s_ashr_i32 s17, s16, 31
	s_nop 0
	v_addc_co_u32_e32 v31, vcc, 0, v55, vcc
	v_add_co_u32_e32 v34, vcc, s41, v54
	global_load_dwordx4 v[26:29], v[54:55], off nt
	s_nop 0
	global_load_dwordx4 v[30:33], v[30:31], off nt
	v_addc_co_u32_e32 v35, vcc, 0, v55, vcc
	v_add_co_u32_e32 v38, vcc, s42, v54
	s_lshl_b64 s[16:17], s[16:17], 1
	s_nop 0
	v_addc_co_u32_e32 v39, vcc, 0, v55, vcc
	v_add_co_u32_e32 v42, vcc, s43, v54
	global_load_dwordx4 v[34:37], v[34:35], off nt
	s_nop 0
	global_load_dwordx4 v[38:41], v[38:39], off nt
	v_addc_co_u32_e32 v43, vcc, 0, v55, vcc
	v_add_co_u32_e32 v46, vcc, s44, v54
	v_or_b32_e32 v58, s14, v6
	s_nop 0
	v_addc_co_u32_e32 v47, vcc, 0, v55, vcc
	global_load_dwordx4 v[42:45], v[42:43], off nt
	s_nop 0
	global_load_dwordx4 v[46:49], v[46:47], off nt
	v_add_co_u32_e32 v50, vcc, s45, v54
	s_add_u32 s16, s47, s16
	s_nop 0
	v_addc_co_u32_e32 v51, vcc, 0, v55, vcc
	global_load_dwordx4 v[50:53], v[50:51], off nt
	v_add_co_u32_e32 v54, vcc, s46, v54
	v_mov_b32_e32 v5, v3
	s_nop 0
	v_addc_co_u32_e32 v55, vcc, 0, v55, vcc
	global_load_dwordx4 v[54:57], v[54:55], off nt
	v_ashrrev_i32_e32 v59, 31, v58
	s_addc_u32 s17, s48, s17
	v_lshlrev_b64 v[58:59], 12, v[58:59]
	v_lshl_add_u64 v[62:63], s[16:17], 0, v[4:5]
	v_or_b32_e32 v60, s14, v7
	v_ashrrev_i32_e32 v61, 31, v60
	v_readlane_b32 s54, v253, 28
	v_readlane_b32 s55, v253, 29
	v_readlane_b32 s56, v253, 30
	v_readlane_b32 s57, v253, 31
	v_readlane_b32 s58, v253, 32
	v_readlane_b32 s59, v253, 33
	v_readlane_b32 s60, v253, 34
	v_readlane_b32 s61, v253, 35
	v_readlane_b32 s62, v253, 36
	v_readlane_b32 s63, v253, 37
	v_readlane_b32 s64, v253, 38
	v_readlane_b32 s65, v253, 39
	v_readlane_b32 s66, v253, 40
	v_readlane_b32 s67, v253, 41
	s_waitcnt vmcnt(7)
	ds_write2_b32 v11, v26, v27 offset1:1
	ds_write2_b32 v11, v28, v29 offset0:2 offset1:3
	s_waitcnt vmcnt(6)
	ds_write2_b32 v12, v30, v31 offset1:1
	ds_write2_b32 v13, v32, v33 offset1:1
	s_waitcnt vmcnt(5)
	ds_write2_b32 v14, v34, v35 offset1:1
	ds_write2_b32 v15, v36, v37 offset1:1
	s_waitcnt vmcnt(4)
	ds_write2_b32 v16, v38, v39 offset1:1
	ds_write2_b32 v17, v40, v41 offset1:1
	s_waitcnt vmcnt(3)
	ds_write2_b32 v18, v42, v43 offset1:1
	ds_write2_b32 v19, v44, v45 offset1:1
	s_waitcnt vmcnt(2)
	ds_write2_b32 v20, v46, v47 offset1:1
	ds_write2_b32 v21, v48, v49 offset1:1
	s_waitcnt vmcnt(1)
	ds_write2_b32 v22, v50, v51 offset1:1
	ds_write2_b32 v23, v52, v53 offset1:1
	s_waitcnt vmcnt(0)
	ds_write2_b32 v24, v54, v55 offset1:1
	ds_write2_b32 v25, v56, v57 offset1:1
	s_waitcnt lgkmcnt(0)
	ds_read2_b32 v[30:31], v10 offset0:33 offset1:41
	ds_read2_b32 v[32:33], v10 offset1:8
	ds_read2_b32 v[34:35], v10 offset0:66 offset1:74
	ds_read2_b32 v[36:37], v10 offset0:99 offset1:107
	ds_read2_b32 v[38:39], v10 offset0:132 offset1:140
	ds_read2_b32 v[40:41], v10 offset0:165 offset1:173
	ds_read2_b32 v[42:43], v10 offset0:198 offset1:206
	ds_read2_b32 v[44:45], v10 offset0:231 offset1:239
	v_lshl_add_u64 v[46:47], v[62:63], 0, v[58:59]
	s_waitcnt lgkmcnt(6)
	v_cvt_pk_bf16_f32 v26, v32, v30
	s_waitcnt lgkmcnt(4)
	v_cvt_pk_bf16_f32 v27, v34, v36
	s_waitcnt lgkmcnt(2)
	v_cvt_pk_bf16_f32 v28, v38, v40
	s_waitcnt lgkmcnt(0)
	v_cvt_pk_bf16_f32 v29, v42, v44
	global_store_dwordx4 v[46:47], v[26:29], off
	v_cvt_pk_bf16_f32 v30, v33, v31
	v_cvt_pk_bf16_f32 v31, v35, v37
	v_cvt_pk_bf16_f32 v32, v39, v41
	v_cvt_pk_bf16_f32 v33, v43, v45
	v_lshlrev_b64 v[26:27], 12, v[60:61]
	ds_read2_b32 v[34:35], v10 offset0:49 offset1:57
	ds_read2_b32 v[36:37], v10 offset0:16 offset1:24
	ds_read2_b32 v[38:39], v10 offset0:82 offset1:90
	ds_read2_b32 v[40:41], v10 offset0:115 offset1:123
	ds_read2_b32 v[42:43], v10 offset0:148 offset1:156
	ds_read2_b32 v[44:45], v10 offset0:181 offset1:189
	ds_read2_b32 v[46:47], v10 offset0:214 offset1:222
	ds_read2_b32 v[48:49], v10 offset0:247 offset1:255
	v_lshl_add_u64 v[26:27], v[62:63], 0, v[26:27]
	global_store_dwordx4 v[26:27], v[30:33], off
	s_waitcnt lgkmcnt(6)
	v_cvt_pk_bf16_f32 v26, v36, v34
	s_waitcnt lgkmcnt(4)
	v_cvt_pk_bf16_f32 v27, v38, v40
	v_or_b32_e32 v30, s14, v8
	v_ashrrev_i32_e32 v31, 31, v30
	v_lshlrev_b64 v[30:31], 12, v[30:31]
	s_waitcnt lgkmcnt(2)
	v_cvt_pk_bf16_f32 v28, v42, v44
	s_waitcnt lgkmcnt(0)
	v_cvt_pk_bf16_f32 v29, v46, v48
	v_lshl_add_u64 v[30:31], v[62:63], 0, v[30:31]
	global_store_dwordx4 v[30:31], v[26:29], off
	v_or_b32_e32 v30, s14, v9
	v_ashrrev_i32_e32 v31, 31, v30
	v_lshlrev_b64 v[30:31], 12, v[30:31]
	v_cvt_pk_bf16_f32 v26, v37, v35
	v_cvt_pk_bf16_f32 v27, v39, v41
	v_cvt_pk_bf16_f32 v28, v43, v45
	v_cvt_pk_bf16_f32 v29, v47, v49
	v_lshl_add_u64 v[30:31], v[62:63], 0, v[30:31]
	global_store_dwordx4 v[30:31], v[26:29], off
	s_waitcnt lgkmcnt(0)
	s_branch .LBB1_25

.LBB1_394:
	s_add_u32 s30, s86, s26
	s_addc_u32 s31, s87, s27
	s_and_b64 s[40:41], s[36:37], exec
	v_mov_b32_e32 v0, 0
	s_cselect_b32 s67, s31, s39
	s_cselect_b32 s68, s30, s38
	s_mov_b32 s44, 0
	s_mov_b64 s[40:41], 0
	s_mov_b64 s[42:43], -1
	v_mov_b32_e32 v1, v0
	v_mov_b32_e32 v2, v0
	v_mov_b32_e32 v3, v0
	v_mov_b32_e32 v4, v0
	v_mov_b32_e32 v5, v0
	v_mov_b32_e32 v6, v0
	v_mov_b32_e32 v7, v0
	v_mov_b32_e32 v8, v0
	v_mov_b32_e32 v9, v0
	v_mov_b32_e32 v10, v0
	v_mov_b32_e32 v11, v0
	v_mov_b32_e32 v12, v0
	v_mov_b32_e32 v13, v0
	v_mov_b32_e32 v14, v0
	v_mov_b32_e32 v15, v0
	v_mov_b32_e32 v24, v0
	v_mov_b32_e32 v25, v0
	v_mov_b32_e32 v26, v0
	v_mov_b32_e32 v27, v0
	v_mov_b32_e32 v28, v0
	v_mov_b32_e32 v29, v0
	v_mov_b32_e32 v30, v0
	v_mov_b32_e32 v31, v0
	v_mov_b32_e32 v40, v0
	v_mov_b32_e32 v41, v0
	v_mov_b32_e32 v42, v0
	v_mov_b32_e32 v43, v0
	v_mov_b32_e32 v44, v0
	v_mov_b32_e32 v45, v0
	v_mov_b32_e32 v46, v0
	v_mov_b32_e32 v47, v0
	v_mov_b32_e32 v16, v0
	v_mov_b32_e32 v17, v0
	v_mov_b32_e32 v18, v0
	v_mov_b32_e32 v19, v0
	v_mov_b32_e32 v20, v0
	v_mov_b32_e32 v21, v0
	v_mov_b32_e32 v22, v0
	v_mov_b32_e32 v23, v0
	v_mov_b32_e32 v32, v0
	v_mov_b32_e32 v33, v0
	v_mov_b32_e32 v34, v0
	v_mov_b32_e32 v35, v0
	v_mov_b32_e32 v36, v0
	v_mov_b32_e32 v37, v0
	v_mov_b32_e32 v38, v0
	v_mov_b32_e32 v39, v0
	v_mov_b32_e32 v48, v0
	v_mov_b32_e32 v49, v0
	v_mov_b32_e32 v50, v0
	v_mov_b32_e32 v51, v0
	v_mov_b32_e32 v52, v0
	v_mov_b32_e32 v53, v0
	v_mov_b32_e32 v54, v0
	v_mov_b32_e32 v55, v0
	v_mov_b32_e32 v56, v0
	v_mov_b32_e32 v57, v0
	v_mov_b32_e32 v58, v0
	v_mov_b32_e32 v59, v0
	v_mov_b32_e32 v60, v0
	v_mov_b32_e32 v61, v0
	v_mov_b32_e32 v62, v0
	v_mov_b32_e32 v63, v0
	v_mov_b32_e32 v64, v0
	v_mov_b32_e32 v65, v0
	v_mov_b32_e32 v66, v0
	v_mov_b32_e32 v67, v0
	v_mov_b32_e32 v68, v0
	v_mov_b32_e32 v69, v0
	v_mov_b32_e32 v70, v0
	v_mov_b32_e32 v71, v0
	v_mov_b32_e32 v72, v0
	v_mov_b32_e32 v73, v0
	v_mov_b32_e32 v74, v0
	v_mov_b32_e32 v75, v0
	v_mov_b32_e32 v76, v0
	v_mov_b32_e32 v77, v0
	v_mov_b32_e32 v78, v0
	v_mov_b32_e32 v79, v0
	v_mov_b32_e32 v88, v0
	v_mov_b32_e32 v89, v0
	v_mov_b32_e32 v90, v0
	v_mov_b32_e32 v91, v0
	v_mov_b32_e32 v92, v0
	v_mov_b32_e32 v93, v0
	v_mov_b32_e32 v94, v0
	v_mov_b32_e32 v95, v0
	v_mov_b32_e32 v104, v0
	v_mov_b32_e32 v105, v0
	v_mov_b32_e32 v106, v0
	v_mov_b32_e32 v107, v0
	v_mov_b32_e32 v108, v0
	v_mov_b32_e32 v109, v0
	v_mov_b32_e32 v110, v0
	v_mov_b32_e32 v111, v0
	v_mov_b32_e32 v80, v0
	v_mov_b32_e32 v81, v0
	v_mov_b32_e32 v82, v0
	v_mov_b32_e32 v83, v0
	v_mov_b32_e32 v84, v0
	v_mov_b32_e32 v85, v0
	v_mov_b32_e32 v86, v0
	v_mov_b32_e32 v87, v0
	v_mov_b32_e32 v96, v0
	v_mov_b32_e32 v97, v0
	v_mov_b32_e32 v98, v0
	v_mov_b32_e32 v99, v0
	v_mov_b32_e32 v100, v0
	v_mov_b32_e32 v101, v0
	v_mov_b32_e32 v102, v0
	v_mov_b32_e32 v103, v0
	v_mov_b32_e32 v114, v0
	v_mov_b32_e32 v115, v0
	v_mov_b32_e32 v116, v0
	v_mov_b32_e32 v117, v0
	v_mov_b32_e32 v118, v0
	v_mov_b32_e32 v119, v0
	v_mov_b32_e32 v120, v0
	v_mov_b32_e32 v121, v0
	v_mov_b32_e32 v122, v0
	v_mov_b32_e32 v123, v0
	v_mov_b32_e32 v124, v0
	v_mov_b32_e32 v125, v0
	v_mov_b32_e32 v126, v0
	v_mov_b32_e32 v127, v0
	v_mov_b32_e32 v128, v0
	v_mov_b32_e32 v129, v0

.LBB1_410:
	s_add_u32 s30, s84, s18
	s_addc_u32 s31, s85, s19
	s_and_b64 s[38:39], s[26:27], exec
	v_mov_b32_e32 v0, 0
	s_cselect_b32 s67, s31, s37
	s_cselect_b32 s68, s30, s36
	s_mov_b32 s42, 0
	s_mov_b64 s[38:39], 0
	s_mov_b64 s[40:41], -1
	v_mov_b32_e32 v1, v0
	v_mov_b32_e32 v2, v0
	v_mov_b32_e32 v3, v0
	v_mov_b32_e32 v4, v0
	v_mov_b32_e32 v5, v0
	v_mov_b32_e32 v6, v0
	v_mov_b32_e32 v7, v0
	v_mov_b32_e32 v8, v0
	v_mov_b32_e32 v9, v0
	v_mov_b32_e32 v10, v0
	v_mov_b32_e32 v11, v0
	v_mov_b32_e32 v12, v0
	v_mov_b32_e32 v13, v0
	v_mov_b32_e32 v14, v0
	v_mov_b32_e32 v15, v0
	v_mov_b32_e32 v24, v0
	v_mov_b32_e32 v25, v0
	v_mov_b32_e32 v26, v0
	v_mov_b32_e32 v27, v0
	v_mov_b32_e32 v28, v0
	v_mov_b32_e32 v29, v0
	v_mov_b32_e32 v30, v0
	v_mov_b32_e32 v31, v0
	v_mov_b32_e32 v40, v0
	v_mov_b32_e32 v41, v0
	v_mov_b32_e32 v42, v0
	v_mov_b32_e32 v43, v0
	v_mov_b32_e32 v44, v0
	v_mov_b32_e32 v45, v0
	v_mov_b32_e32 v46, v0
	v_mov_b32_e32 v47, v0
	v_mov_b32_e32 v16, v0
	v_mov_b32_e32 v17, v0
	v_mov_b32_e32 v18, v0
	v_mov_b32_e32 v19, v0
	v_mov_b32_e32 v20, v0
	v_mov_b32_e32 v21, v0
	v_mov_b32_e32 v22, v0
	v_mov_b32_e32 v23, v0
	v_mov_b32_e32 v32, v0
	v_mov_b32_e32 v33, v0
	v_mov_b32_e32 v34, v0
	v_mov_b32_e32 v35, v0
	v_mov_b32_e32 v36, v0
	v_mov_b32_e32 v37, v0
	v_mov_b32_e32 v38, v0
	v_mov_b32_e32 v39, v0
	v_mov_b32_e32 v48, v0
	v_mov_b32_e32 v49, v0
	v_mov_b32_e32 v50, v0
	v_mov_b32_e32 v51, v0
	v_mov_b32_e32 v52, v0
	v_mov_b32_e32 v53, v0
	v_mov_b32_e32 v54, v0
	v_mov_b32_e32 v55, v0
	v_mov_b32_e32 v56, v0
	v_mov_b32_e32 v57, v0
	v_mov_b32_e32 v58, v0
	v_mov_b32_e32 v59, v0
	v_mov_b32_e32 v60, v0
	v_mov_b32_e32 v61, v0
	v_mov_b32_e32 v62, v0
	v_mov_b32_e32 v63, v0
	v_mov_b32_e32 v64, v0
	v_mov_b32_e32 v65, v0
	v_mov_b32_e32 v66, v0
	v_mov_b32_e32 v67, v0
	v_mov_b32_e32 v68, v0
	v_mov_b32_e32 v69, v0
	v_mov_b32_e32 v70, v0
	v_mov_b32_e32 v71, v0
	v_mov_b32_e32 v72, v0
	v_mov_b32_e32 v73, v0
	v_mov_b32_e32 v74, v0
	v_mov_b32_e32 v75, v0
	v_mov_b32_e32 v76, v0
	v_mov_b32_e32 v77, v0
	v_mov_b32_e32 v78, v0
	v_mov_b32_e32 v79, v0
	v_mov_b32_e32 v88, v0
	v_mov_b32_e32 v89, v0
	v_mov_b32_e32 v90, v0
	v_mov_b32_e32 v91, v0
	v_mov_b32_e32 v92, v0
	v_mov_b32_e32 v93, v0
	v_mov_b32_e32 v94, v0
	v_mov_b32_e32 v95, v0
	v_mov_b32_e32 v104, v0
	v_mov_b32_e32 v105, v0
	v_mov_b32_e32 v106, v0
	v_mov_b32_e32 v107, v0
	v_mov_b32_e32 v108, v0
	v_mov_b32_e32 v109, v0
	v_mov_b32_e32 v110, v0
	v_mov_b32_e32 v111, v0
	v_mov_b32_e32 v80, v0
	v_mov_b32_e32 v81, v0
	v_mov_b32_e32 v82, v0
	v_mov_b32_e32 v83, v0
	v_mov_b32_e32 v84, v0
	v_mov_b32_e32 v85, v0
	v_mov_b32_e32 v86, v0
	v_mov_b32_e32 v87, v0
	v_mov_b32_e32 v96, v0
	v_mov_b32_e32 v97, v0
	v_mov_b32_e32 v98, v0
	v_mov_b32_e32 v99, v0
	v_mov_b32_e32 v100, v0
	v_mov_b32_e32 v101, v0
	v_mov_b32_e32 v102, v0
	v_mov_b32_e32 v103, v0
	v_mov_b32_e32 v114, v0
	v_mov_b32_e32 v115, v0
	v_mov_b32_e32 v116, v0
	v_mov_b32_e32 v117, v0
	v_mov_b32_e32 v118, v0
	v_mov_b32_e32 v119, v0
	v_mov_b32_e32 v120, v0
	v_mov_b32_e32 v121, v0
	v_mov_b32_e32 v122, v0
	v_mov_b32_e32 v123, v0
	v_mov_b32_e32 v124, v0
	v_mov_b32_e32 v125, v0
	v_mov_b32_e32 v126, v0
	v_mov_b32_e32 v127, v0
	v_mov_b32_e32 v128, v0
	v_mov_b32_e32 v129, v0
